# stats exchange: polling wave invalidates L1 before the poll loop instead of after
# baseline (speedup 1.0000x reference)
.LBB0_550:
	s_or_b64 exec, exec, s[46:47]
	s_cmp_gt_u32 s57, 63
	s_cbranch_scc1 .LBB0_580
	buffer_inv sc1
	s_memrealtime s[46:47]
	s_lshl_b32 s52, s66, 6
	s_ashr_i32 s53, s52, 31
	s_lshl_b64 s[52:53], s[52:53], 2
	s_add_u32 s62, s51, s52
	s_addc_u32 s63, s50, s53
	s_branch .LBB0_554

.LBB0_577:
	s_and_saveexec_b64 s[46:47], s[44:45]
	v_cndmask_b32_e64 v32, 0, 1, s[52:53]
	ds_write_b32 v33, v32 offset:10240
	s_or_b64 exec, exec, s[46:47]
	v_readlane_b32 s64, v255, 29
	v_readlane_b32 s65, v255, 30

.LBB0_878:
	s_or_b64 exec, exec, s[46:47]
	s_cmp_gt_u32 s0, 63
	s_cbranch_scc1 .LBB0_908
	buffer_inv sc1
	s_memrealtime s[46:47]
	s_lshl_b32 s40, s50, 6
	s_ashr_i32 s41, s40, 31
	s_lshl_b64 s[40:41], s[40:41], 2
	s_add_u32 s52, s59, s40
	s_addc_u32 s53, s58, s41
	s_branch .LBB0_882

.LBB0_905:
	s_and_saveexec_b64 s[46:47], s[44:45]
	v_cndmask_b32_e64 v32, 0, 1, s[54:55]
	ds_write_b32 v33, v32 offset:10240
	s_or_b64 exec, exec, s[46:47]
